# v063 + split grid barrier before GEMM phases: arrive, run the phase setup, wait right before the first LDS-DMA load
# baseline (speedup 1.0000x reference)
.LBB0_123:
	s_lshl_b32 s8, s3, 8
	s_add_u32 s8, s34, s8
	s_addc_u32 s9, s35, 0
	v_mov_b32_e32 v3, 0x1000
	v_mov_b32_e32 v5, 1
	global_atomic_add v5, v3, v5, s[8:9] offset:1024 sc0
	v_cvt_f32_u32_e32 v3, v4
	v_sub_u32_e32 v6, 0, v4
	v_rcp_iflag_f32_e32 v3, v3
	s_nop 0
	v_mul_f32_e32 v3, 0x4f7ffffe, v3
	v_cvt_u32_f32_e32 v3, v3
	v_mul_lo_u32 v6, v6, v3
	v_mul_hi_u32 v6, v3, v6
	v_add_u32_e32 v3, v3, v6
	s_waitcnt vmcnt(0)
	v_mul_hi_u32 v3, v5, v3
	v_mul_lo_u32 v6, v3, v4
	v_sub_u32_e32 v6, v5, v6
	v_add_u32_e32 v7, 1, v3
	v_cmp_ge_u32_e32 vcc, v6, v4
	v_add_u32_e32 v5, 1, v5
	s_nop 0
	v_cndmask_b32_e32 v3, v3, v7, vcc
	v_sub_u32_e32 v7, v6, v4
	v_cndmask_b32_e32 v6, v6, v7, vcc
	v_add_u32_e32 v7, 1, v3
	v_cmp_ge_u32_e32 vcc, v6, v4
	s_nop 1
	v_cndmask_b32_e32 v3, v3, v7, vcc
	v_mul_lo_u32 v6, v4, v3
	v_add_u32_e32 v4, v6, v4
	v_cmp_ne_u32_e32 vcc, v5, v4
	s_and_saveexec_b64 s[14:15], vcc
	s_xor_b64 s[14:15], exec, s[14:15]
	s_cbranch_execz .LBB0_137
	s_waitcnt lgkmcnt(0)
	v_mad_u32_u24 v6, v3, v2, v2
	s_nop 0
	v_readfirstlane_b32 s95, v6
.LBB0_137:
	s_andn2_saveexec_b64 s[14:15], s[14:15]
	s_cbranch_execz .LBB0_155
	buffer_wbl2 sc1
	s_waitcnt lgkmcnt(0)
	v_mad_u32_u24 v6, v3, v2, v2
	s_waitcnt vmcnt(0)
	v_mov_b32_e32 v4, 0x1d6c5000
	v_mov_b32_e32 v5, 1
	global_atomic_add v4, v5, s[38:39] offset:1024
	v_readfirstlane_b32 s95, v6
.LBB0_155:
	s_or_b64 exec, exec, s[6:7]
	s_waitcnt lgkmcnt(0)
.LBB0_156:
	s_cmp_lt_i32 s40, 3
	s_cselect_b64 s[6:7], -1, 0
	s_and_b64 s[8:9], s[6:7], s[4:5]
	s_andn2_b64 vcc, exec, s[8:9]
	s_cbranch_vccnz .LBB0_233
	s_and_saveexec_b64 s[4:5], s[26:27]
	s_cbranch_execz .LBB0_159
	s_add_u32 s14, s38, 0x53c2000
	s_addc_u32 s15, s39, 0
	s_add_u32 s6, s38, 0x97c2000
	s_addc_u32 s7, s39, 0
	s_add_i32 s16, 0, 0x20000
	v_mov_b32_e32 v2, s14
	v_mov_b32_e32 v3, s15
	v_mov_b32_e32 v4, s38
	v_mov_b32_e32 v5, s39
	v_mov_b32_e32 v6, s16
	s_mov_b32 s14, 0
	ds_write_b128 v6, v[2:5]
	s_add_i32 s16, 0, 0x20010
	v_mov_b64_e32 v[4:5], s[6:7]
	s_movk_i32 s6, 0x88
	s_movk_i32 s15, 0xb00
	v_mov_b32_e32 v2, s16
	s_mov_b32 s7, 22
	s_add_i32 s16, 0, 0x20018
	ds_write_b64 v2, v[4:5]
	v_mov_b32_e32 v6, s16
	v_mov_b64_e32 v[2:3], s[6:7]
	v_mov_b64_e32 v[4:5], s[14:15]
	s_add_i32 s6, 0, 0x20028
	ds_write2_b64 v6, v[2:3], v[4:5] offset1:1
	v_mov_b32_e32 v2, 1
	v_mov_b32_e32 v3, 16
	v_mov_b32_e32 v4, s6
	ds_write_b64 v4, v[2:3]

.LBB0_162:
	v_ashrrev_i32_e32 v7, 31, v14
	v_lshrrev_b32_e32 v7, 26, v7
	v_add_u32_e32 v7, v14, v7
	v_ashrrev_i32_e32 v15, 6, v7
	v_bfe_i32 v7, v14, 27, 1
	v_lshlrev_b32_e32 v6, 4, v14
	v_lshrrev_b32_e32 v7, 22, v7
	v_add_u32_e32 v7, v6, v7
	v_and_b32_e32 v7, 0xfffffc00, v7
	v_sub_u32_e32 v7, v6, v7
	v_lshrrev_b32_e32 v8, 4, v7
	v_bitop3_b32 v8, v8, v7, 32 bitop3:0x6c
	v_ashrrev_i32_e32 v7, 31, v7
	v_lshrrev_b32_e32 v7, 26, v7
	v_add_u32_e32 v7, v8, v7
	v_ashrrev_i32_e32 v16, 6, v7
	v_lshlrev_b32_e32 v9, 3, v15
	v_mul_i32_i24_e32 v10, 64, v16
	v_and_b32_e32 v9, -16, v9
	v_sub_u32_e32 v8, v8, v10
	v_mov_b32_e32 v10, 1
	v_add_u32_e32 v7, v16, v9
	v_lshlrev_b32_e32 v9, 5, v15
	v_ashrrev_i16_sdwa v8, v10, sext(v8) dst_sel:DWORD dst_unused:UNUSED_PAD src0_sel:DWORD src1_sel:BYTE_0
	v_and_b32_e32 v9, 32, v9
	v_bfe_i32 v17, v8, 0, 16
	v_and_b32_e32 v12, 3, v16
	s_mov_b32 s5, 0x1fffe0
	v_add_lshl_u32 v9, v9, v17, 1
	v_add_u32_e32 v6, 0x2000, v6
	v_lshlrev_b32_e32 v8, 1, v7
	v_lshrrev_b32_e32 v11, 2, v7
	v_and_or_b32 v12, v7, s5, v12
	v_lshl_add_u32 v130, v7, 11, v9
	v_ashrrev_i32_e32 v7, 31, v6
	v_lshrrev_b32_e32 v7, 22, v7
	v_add_u32_e32 v7, v6, v7
	v_ashrrev_i32_e32 v18, 10, v7
	v_mul_i32_i24_e32 v7, 0x400, v18
	v_sub_u32_e32 v6, v6, v7
	v_and_b32_e32 v8, 24, v8
	v_and_b32_e32 v11, 4, v11
	v_lshrrev_b32_e32 v7, 4, v6
	v_or3_b32 v8, v12, v11, v8
	v_bitop3_b32 v6, v7, v6, 32 bitop3:0x6c
	v_lshl_add_u32 v132, v8, 11, v9
	v_ashrrev_i32_e32 v8, 31, v6
	v_lshrrev_b32_e32 v8, 26, v8
	v_add_u32_e32 v8, v6, v8
	v_lshlrev_b32_e32 v7, 3, v18
	v_ashrrev_i32_e32 v19, 6, v8
	v_and_b32_e32 v8, 0xc0, v8
	v_and_b32_e32 v7, -16, v7
	v_sub_u32_e32 v6, v6, v8
	s_ashr_i32 s4, s16, 6
	v_add_u32_e32 v7, v19, v7
	v_ashrrev_i16_sdwa v6, v10, sext(v6) dst_sel:DWORD dst_unused:UNUSED_PAD src0_sel:DWORD src1_sel:BYTE_0
	v_lshlrev_b32_e32 v9, 5, v18
	v_bfe_i32 v20, v6, 0, 16
	v_lshlrev_b32_e32 v6, 1, v7
	v_lshrrev_b32_e32 v8, 2, v7
	v_and_b32_e32 v10, 3, v19
	s_lshl_b32 s47, s4, 10
	v_and_b32_e32 v9, 32, v9
	v_and_b32_e32 v6, 24, v6
	v_and_b32_e32 v8, 4, v8
	v_and_or_b32 v10, v7, s5, v10
	s_add_i32 s57, s47, 0
	v_or3_b32 v6, v10, v8, v6
	v_add_lshl_u32 v8, v9, v20, 1
	s_add_i32 m0, s57, 0x10000
	v_readfirstlane_b32 s14, v4
	v_readfirstlane_b32 s15, v5
	v_lshl_add_u32 v136, v6, 11, v8
	v_lshl_add_u32 v134, v7, 11, v8
	s_add_i32 s62, s57, 0x2000
	s_add_i32 s63, s57, 0x4000
	s_add_i32 s64, s57, 0x6000
	s_and_saveexec_b64 s[96:97], s[26:27]
	s_cbranch_execz .Lmy_w_1
	s_add_u32 s98, s38, 0x1d6c5400
	s_addc_u32 s99, s39, 0
	v_mov_b32_e32 v234, 0
	s_mov_b32 s94, 0
.Lmy_ws_1:
	global_load_dword v235, v234, s[98:99] sc1
	s_waitcnt vmcnt(0)
	v_subrev_u32_e32 v235, s95, v235
	v_cmp_gt_i32_e32 vcc, 0, v235
	s_cbranch_vccz .Lmy_wd_1
	s_sleep 1
	s_add_i32 s94, s94, 1
	s_cmp_lt_u32 s94, 0x100000
	s_cbranch_scc1 .Lmy_ws_1

.Lmy_w_1:
	s_or_b64 exec, exec, s[96:97]
	s_barrier
	global_load_lds_dwordx4 v132, s[14:15]
	s_add_i32 m0, s57, 0x12000
	s_ashr_i32 s5, s16, 8
	global_load_lds_dwordx4 v136, s[14:15]
	s_mov_b64 s[14:15], 0x40000
	v_lshl_add_u64 v[6:7], v[4:5], 0, s[14:15]
	s_add_i32 m0, s57, 0x14000
	v_readfirstlane_b32 s18, v6
	v_readfirstlane_b32 s19, v7
	v_lshl_add_u64 v[6:7], v[2:3], 0, s[14:15]
	v_mov_b32_e32 v139, 0
	v_mov_b32_e32 v133, v139
	v_mov_b32_e32 v137, v139
	v_mov_b32_e32 v131, v139
	global_load_lds_dwordx4 v132, s[18:19]
	s_add_i32 m0, s57, 0x16000
	v_mov_b32_e32 v135, v139
	global_load_lds_dwordx4 v136, s[18:19]
	v_readfirstlane_b32 s18, v2
	v_readfirstlane_b32 s19, v3
	s_mov_b32 m0, s57
	s_cmp_eq_u32 s5, 1
	s_mov_b32 s17, 0
	v_lshl_add_u64 v[12:13], v[4:5], 0, v[132:133]
	v_lshl_add_u64 v[10:11], v[4:5], 0, v[136:137]
	global_load_lds_dwordx4 v130, s[18:19]
	s_mov_b32 m0, s62
	v_lshl_add_u64 v[8:9], v[2:3], 0, v[134:135]
	global_load_lds_dwordx4 v134, s[18:19]
	v_readfirstlane_b32 s18, v6
	v_readfirstlane_b32 s19, v7
	s_mov_b32 m0, s63
	v_lshl_add_u64 v[6:7], v[2:3], 0, v[130:131]
	s_nop 2
	global_load_lds_dwordx4 v130, s[18:19]
	s_mov_b32 m0, s64
	s_nop 0
	global_load_lds_dwordx4 v134, s[18:19]
	s_cselect_b64 s[18:19], -1, 0
	s_cmp_lg_u32 s5, 1
	s_cbranch_scc1 .LBB0_164
	s_barrier

.LBB0_282:
	s_or_b64 exec, exec, s[6:7]
	s_waitcnt lgkmcnt(0)
.LBB0_283:
	s_cmp_lt_i32 s40, 4
	s_cselect_b64 s[6:7], -1, 0
	s_and_b64 s[14:15], s[6:7], s[4:5]
	s_andn2_b64 vcc, exec, s[14:15]
	s_cbranch_vccnz .LBB0_372
	s_abs_i32 s22, s42
	v_cvt_f32_u32_e32 v2, s22
	s_sub_i32 s24, 0, s22
	s_mov_b32 s5, 0
	s_ashr_i32 s23, s42, 31
	v_rcp_iflag_f32_e32 v2, v2
	s_nop 0
	v_mul_f32_e32 v3, 0x4f7ffffe, v2
	v_cvt_u32_f32_e32 v3, v3
	s_nop 0
	v_readfirstlane_b32 s4, v3
	s_mul_i32 s6, s24, s4
	s_mul_hi_u32 s6, s4, s6
	s_add_i32 s4, s4, s6
	s_lshl_b64 s[6:7], s[4:5], 9
	s_and_saveexec_b64 s[8:9], s[26:27]
	s_cbranch_execz .LBB0_286
	s_add_u32 s4, s38, 0x147c2000
	s_addc_u32 s6, s39, 0
	s_add_u32 s16, s38, 0x2c00000
	s_addc_u32 s17, s39, 0
	s_add_u32 s20, s38, 0x97c2000
	s_addc_u32 s21, s39, 0
	s_add_u32 s18, s38, 0x152c2000
	s_addc_u32 s19, s39, 0
	v_mov_b32_e32 v4, s20
	s_add_i32 s20, 0, 0x20000
	v_mov_b32_e32 v5, s21
	v_mov_b32_e32 v6, s16
	v_mov_b32_e32 v7, s17
	v_mov_b32_e32 v3, s20
	s_mov_b32 s16, 0
	ds_write_b128 v3, v[4:7]
	s_add_i32 s20, 0, 0x20010
	v_mov_b64_e32 v[4:5], s[18:19]
	s_movk_i32 s18, 0x80
	s_movk_i32 s17, 0x400
	v_mov_b32_e32 v3, s20
	s_mov_b32 s19, 4
	s_add_i32 s20, 0, 0x20018
	ds_write_b64 v3, v[4:5]
	v_mov_b32_e32 v3, s20
	v_mov_b64_e32 v[4:5], s[18:19]
	v_mov_b64_e32 v[8:9], s[16:17]
	s_add_i32 s18, 0, 0x20028
	ds_write2_b64 v3, v[4:5], v[8:9] offset1:1
	v_mov_b32_e32 v4, 4
	v_mov_b32_e32 v5, 44
	v_mov_b32_e32 v3, s18
	ds_write_b64 v3, v[4:5]
	v_mov_b32_e32 v4, s4
	s_add_i32 s4, 0, 0x20030
	v_mov_b32_e32 v5, s6
	v_mov_b32_e32 v3, s4
	s_add_i32 s4, 0, 0x20040
	ds_write_b128 v3, v[4:7]
	v_mov_b32_e32 v3, s4
	v_mov_b64_e32 v[4:5], s[36:37]
	s_movk_i32 s28, 0x200
	s_mov_b32 s29, s17
	s_add_i32 s4, 0, 0x20048
	ds_write_b64 v3, v[4:5]
	v_mov_b32_e32 v3, s4
	v_mov_b64_e32 v[6:7], s[28:29]
	s_mov_b32 s29, 12
	s_mov_b32 s28, s16
	s_add_i32 s4, 0, 0x20058
	s_mov_b32 s20, 8
	s_mov_b32 s21, s19
	v_mov_b64_e32 v[8:9], s[28:29]
	s_add_u32 s28, s36, 0x400000
	v_mov_b64_e32 v[4:5], s[20:21]
	s_addc_u32 s29, s37, 0
	ds_write2_b64 v3, v[4:5], v[6:7] offset1:1
	v_mov_b32_e32 v3, s4
	s_add_u32 s4, s38, 0x2c00600
	s_addc_u32 s6, s39, 0
	s_add_u32 s18, s38, 0x147c2600
	s_addc_u32 s21, s39, 0
	v_mov_b32_e32 v6, s4
	s_add_i32 s4, 0, 0x20060
	ds_write_b64 v3, v[8:9]
	v_mov_b32_e32 v4, s18
	v_mov_b32_e32 v5, s21
	v_mov_b32_e32 v7, s6
	v_mov_b32_e32 v3, s4
	s_add_i32 s4, 0, 0x20070
	ds_write_b128 v3, v[4:7]
	v_mov_b32_e32 v3, s4
	v_mov_b64_e32 v[4:5], s[28:29]
	s_add_i32 s4, 0, 0x20078
	ds_write_b64 v3, v[4:5]
	s_movk_i32 s28, 0x220
	s_mov_b32 s29, s17
	v_mov_b32_e32 v3, s4
	s_add_i32 s4, 0, 0x20088
	s_mov_b32 s21, s19
	v_mov_b64_e32 v[6:7], s[28:29]
	s_add_u32 s28, s36, 0x800000
	v_mov_b64_e32 v[4:5], s[20:21]
	s_addc_u32 s29, s37, 0
	ds_write2_b64 v3, v[4:5], v[6:7] offset1:1
	v_mov_b32_e32 v3, s4
	s_add_u32 s4, s38, 0x2c00c00
	s_addc_u32 s6, s39, 0
	s_add_u32 s18, s38, 0x147c2c00
	s_addc_u32 s21, s39, 0
	v_mov_b32_e32 v6, s4
	s_add_i32 s4, 0, 0x20090
	ds_write_b64 v3, v[8:9]
	v_mov_b32_e32 v4, s18
	v_mov_b32_e32 v5, s21
	v_mov_b32_e32 v7, s6
	v_mov_b32_e32 v3, s4
	s_add_i32 s4, 0, 0x200a0
	ds_write_b128 v3, v[4:7]
	v_mov_b32_e32 v3, s4
	v_mov_b64_e32 v[4:5], s[28:29]
	s_movk_i32 s28, 0x240
	s_mov_b32 s29, s17
	s_add_i32 s4, 0, 0x200a8
	ds_write_b64 v3, v[4:5]
	v_mov_b32_e32 v3, s4
	v_mov_b64_e32 v[6:7], s[28:29]
	s_mov_b32 s29, 10
	s_mov_b32 s28, s16
	s_add_i32 s4, 0, 0x200b8
	s_mov_b32 s21, s19
	v_mov_b64_e32 v[8:9], s[28:29]
	s_add_u32 s28, s36, 0xc00000
	v_mov_b64_e32 v[4:5], s[20:21]
	s_addc_u32 s29, s37, 0
	ds_write2_b64 v3, v[4:5], v[6:7] offset1:1
	v_mov_b32_e32 v3, s4
	s_add_u32 s4, s38, 0x2c01100
	s_addc_u32 s6, s39, 0
	s_add_u32 s16, s38, 0x147c3100
	s_addc_u32 s18, s39, 0
	v_mov_b32_e32 v6, s4
	s_add_i32 s4, 0, 0x200c0
	ds_write_b64 v3, v[8:9]
	v_mov_b32_e32 v4, s16
	v_mov_b32_e32 v5, s18
	v_mov_b32_e32 v7, s6
	v_mov_b32_e32 v3, s4
	s_add_i32 s4, 0, 0x200d0
	ds_write_b128 v3, v[4:7]
	v_mov_b32_e32 v3, s4
	v_mov_b64_e32 v[4:5], s[28:29]
	s_movk_i32 s16, 0x260
	s_add_i32 s4, 0, 0x200d8
	ds_write_b64 v3, v[4:5]
	v_mov_b32_e32 v3, s4
	v_mov_b64_e32 v[4:5], s[20:21]
	v_mov_b64_e32 v[6:7], s[16:17]
	s_add_i32 s4, 0, 0x200e8
	ds_write2_b64 v3, v[4:5], v[6:7] offset1:1
	v_mov_b32_e32 v3, s4
	ds_write_b64 v3, v[8:9]

.LBB0_295:
	v_ashrrev_i32_e32 v5, 31, v12
	v_lshrrev_b32_e32 v5, 26, v5
	v_add_u32_e32 v5, v12, v5
	v_ashrrev_i32_e32 v13, 6, v5
	v_bfe_i32 v5, v12, 27, 1
	v_lshlrev_b32_e32 v4, 4, v12
	v_lshrrev_b32_e32 v5, 22, v5
	v_add_u32_e32 v5, v4, v5
	v_and_b32_e32 v5, 0xfffffc00, v5
	v_sub_u32_e32 v5, v4, v5
	v_lshrrev_b32_e32 v6, 4, v5
	v_bitop3_b32 v6, v6, v5, 32 bitop3:0x6c
	v_ashrrev_i32_e32 v5, 31, v5
	v_lshrrev_b32_e32 v5, 26, v5
	v_lshlrev_b32_e32 v7, 3, v13
	v_add_u32_e32 v5, v6, v5
	v_and_b32_e32 v7, -16, v7
	v_ashrrev_i32_e32 v14, 6, v5
	v_add_u32_e32 v5, v14, v7
	v_lshlrev_b32_e32 v7, 5, v13
	v_and_b32_e32 v15, 32, v7
	v_mul_i32_i24_e32 v7, 64, v14
	v_sub_u32_e32 v6, v6, v7
	v_mov_b32_e32 v7, 1
	v_ashrrev_i16_sdwa v6, v7, sext(v6) dst_sel:DWORD dst_unused:UNUSED_PAD src0_sel:DWORD src1_sel:BYTE_0
	v_lshlrev_b32_e32 v8, 1, v5
	v_lshrrev_b32_e32 v9, 2, v5
	v_and_b32_e32 v10, 3, v14
	s_mov_b32 s9, 0xffffe0
	v_bfe_i32 v16, v6, 0, 16
	v_and_b32_e32 v8, 24, v8
	v_and_b32_e32 v9, 4, v9
	v_and_or_b32 v10, v5, s9, v10
	s_movk_i32 s8, 0xb00
	v_add_u32_e32 v6, v15, v16
	v_or3_b32 v8, v10, v9, v8
	v_mul_lo_u32 v5, v5, s8
	v_add_lshl_u32 v130, v6, v5, 1
	v_mul_u32_u24_e32 v5, 0xb00, v8
	v_add_u32_e32 v4, 0x2000, v4
	v_add_lshl_u32 v132, v5, v6, 1
	v_ashrrev_i32_e32 v5, 31, v4
	v_lshrrev_b32_e32 v5, 22, v5
	v_add_u32_e32 v5, v4, v5
	v_ashrrev_i32_e32 v17, 10, v5
	v_mul_i32_i24_e32 v5, 0x400, v17
	v_sub_u32_e32 v4, v4, v5
	v_lshrrev_b32_e32 v5, 4, v4
	v_bitop3_b32 v4, v5, v4, 32 bitop3:0x6c
	v_ashrrev_i32_e32 v6, 31, v4
	v_lshrrev_b32_e32 v6, 26, v6
	v_lshlrev_b32_e32 v5, 3, v17
	v_add_u32_e32 v6, v4, v6
	v_and_b32_e32 v5, -16, v5
	v_ashrrev_i32_e32 v19, 6, v6
	v_and_b32_e32 v6, 0xc0, v6
	v_add_u32_e32 v5, v19, v5
	v_lshlrev_b32_e32 v8, 5, v17
	v_sub_u32_e32 v4, v4, v6
	s_ashr_i32 s5, s4, 6
	v_and_b32_e32 v18, 32, v8
	v_ashrrev_i16_sdwa v4, v7, sext(v4) dst_sel:DWORD dst_unused:UNUSED_PAD src0_sel:DWORD src1_sel:BYTE_0
	v_lshlrev_b32_e32 v6, 1, v5
	v_lshrrev_b32_e32 v7, 2, v5
	v_and_b32_e32 v8, 3, v19
	v_bfe_i32 v20, v4, 0, 16
	v_and_b32_e32 v6, 24, v6
	v_and_b32_e32 v7, 4, v7
	v_and_or_b32 v8, v5, s9, v8
	s_lshl_b32 s54, s5, 10
	v_add_u32_e32 v4, v18, v20
	v_or3_b32 v6, v8, v7, v6
	v_mul_lo_u32 v5, v5, s8
	s_add_i32 s55, s54, 0
	v_add_lshl_u32 v134, v4, v5, 1
	v_mul_u32_u24_e32 v5, 0xb00, v6
	s_add_i32 m0, s55, 0x10000
	v_readfirstlane_b32 s16, v2
	v_readfirstlane_b32 s17, v3
	v_add_lshl_u32 v136, v5, v4, 1
	s_add_i32 s56, s55, 0x2000
	s_add_i32 s57, s55, 0x4000
	s_add_i32 s58, s55, 0x6000
	s_ashr_i32 s9, s4, 8
	s_and_saveexec_b64 s[96:97], s[26:27]
	s_cbranch_execz .Lmy_w_2
	s_add_u32 s98, s38, 0x1d6c5400
	s_addc_u32 s99, s39, 0
	v_mov_b32_e32 v234, 0
	s_mov_b32 s94, 0

.Lmy_w_2:
	s_or_b64 exec, exec, s[96:97]
	s_barrier
	global_load_lds_dwordx4 v132, s[16:17]
	s_add_i32 m0, s55, 0x12000
	v_mov_b32_e32 v139, 0
	global_load_lds_dwordx4 v136, s[16:17]
	s_mov_b64 s[16:17], 0xb0000
	v_lshl_add_u64 v[4:5], v[2:3], 0, s[16:17]
	s_add_i32 m0, s55, 0x14000
	v_readfirstlane_b32 s18, v4
	v_readfirstlane_b32 s19, v5
	v_lshl_add_u64 v[4:5], v[152:153], 0, s[16:17]
	v_mov_b32_e32 v133, v139
	v_mov_b32_e32 v137, v139
	v_mov_b32_e32 v131, v139
	v_mov_b32_e32 v135, v139
	global_load_lds_dwordx4 v132, s[18:19]
	s_add_i32 m0, s55, 0x16000
	s_cmp_eq_u32 s9, 1
	global_load_lds_dwordx4 v136, s[18:19]
	v_readfirstlane_b32 s18, v152
	v_readfirstlane_b32 s19, v153
	s_mov_b32 m0, s55
	s_mov_b32 s59, 0
	v_lshl_add_u64 v[10:11], v[2:3], 0, v[132:133]
	v_lshl_add_u64 v[8:9], v[2:3], 0, v[136:137]
	v_lshl_add_u64 v[6:7], v[152:153], 0, v[134:135]
	global_load_lds_dwordx4 v130, s[18:19]
	s_mov_b32 m0, s56
	s_nop 0
	global_load_lds_dwordx4 v134, s[18:19]
	v_readfirstlane_b32 s18, v4
	v_readfirstlane_b32 s19, v5
	s_mov_b32 m0, s57
	v_lshl_add_u64 v[4:5], v[152:153], 0, v[130:131]
	s_nop 2
	global_load_lds_dwordx4 v130, s[18:19]
	s_mov_b32 m0, s58
	s_nop 0
	global_load_lds_dwordx4 v134, s[18:19]
	s_cselect_b64 s[18:19], -1, 0
	s_cmp_lg_u32 s9, 1
	s_cbranch_scc1 .LBB0_297
	s_barrier

.LBB0_451:
	s_lshl_b32 s8, s3, 8
	s_add_u32 s8, s34, s8
	s_addc_u32 s9, s35, 0
	v_mov_b32_e32 v3, 0x1000
	v_mov_b32_e32 v5, 1
	global_atomic_add v5, v3, v5, s[8:9] offset:1024 sc0
	v_cvt_f32_u32_e32 v3, v4
	v_sub_u32_e32 v6, 0, v4
	v_rcp_iflag_f32_e32 v3, v3
	s_nop 0
	v_mul_f32_e32 v3, 0x4f7ffffe, v3
	v_cvt_u32_f32_e32 v3, v3
	v_mul_lo_u32 v6, v6, v3
	v_mul_hi_u32 v6, v3, v6
	v_add_u32_e32 v3, v3, v6
	s_waitcnt vmcnt(0)
	v_mul_hi_u32 v3, v5, v3
	v_mul_lo_u32 v6, v3, v4
	v_sub_u32_e32 v6, v5, v6
	v_add_u32_e32 v7, 1, v3
	v_cmp_ge_u32_e32 vcc, v6, v4
	v_add_u32_e32 v5, 1, v5
	s_nop 0
	v_cndmask_b32_e32 v3, v3, v7, vcc
	v_sub_u32_e32 v7, v6, v4
	v_cndmask_b32_e32 v6, v6, v7, vcc
	v_add_u32_e32 v7, 1, v3
	v_cmp_ge_u32_e32 vcc, v6, v4
	s_nop 1
	v_cndmask_b32_e32 v3, v3, v7, vcc
	v_mul_lo_u32 v6, v4, v3
	v_add_u32_e32 v4, v6, v4
	v_cmp_ne_u32_e32 vcc, v5, v4
	s_and_saveexec_b64 s[10:11], vcc
	s_xor_b64 s[10:11], exec, s[10:11]
	s_cbranch_execz .LBB0_465
	s_waitcnt lgkmcnt(0)
	v_mad_u32_u24 v6, v3, v2, v2
	s_nop 0
	v_readfirstlane_b32 s95, v6
.LBB0_465:
	s_andn2_saveexec_b64 s[10:11], s[10:11]
	s_cbranch_execz .LBB0_483
	buffer_wbl2 sc1
	s_waitcnt lgkmcnt(0)
	v_mad_u32_u24 v6, v3, v2, v2
	s_waitcnt vmcnt(0)
	v_mov_b32_e32 v4, 0x1d6c5000
	v_mov_b32_e32 v5, 1
	global_atomic_add v4, v5, s[38:39] offset:1024
	v_readfirstlane_b32 s95, v6
.LBB0_483:
	s_or_b64 exec, exec, s[6:7]
	s_waitcnt lgkmcnt(0)
.LBB0_484:
	s_cmp_lt_i32 s40, 6
	s_cselect_b64 s[6:7], -1, 0
	s_and_b64 s[8:9], s[6:7], s[4:5]
	s_andn2_b64 vcc, exec, s[8:9]
	s_cbranch_vccnz .LBB0_561
	s_waitcnt lgkmcnt(0)
	s_and_saveexec_b64 s[10:11], s[26:27]
	s_cbranch_execz .LBB0_487
	s_add_u32 s44, s38, 0x4600000
	s_addc_u32 s45, s39, 0
	s_add_u32 s12, s38, 0xf9c2000
	s_addc_u32 s13, s39, 0
	s_add_u32 s16, s38, 0xf7c2000
	s_addc_u32 s17, s39, 0
	s_add_u32 s46, s38, 0x93c2000
	s_addc_u32 s47, s39, 0
	s_add_u32 s48, s38, 0x4500000
	s_addc_u32 s49, s39, 0
	s_add_u32 s20, s38, 0xd7c2000
	s_addc_u32 s21, s39, 0
	s_add_u32 s22, s38, 0x97c2400
	s_addc_u32 s23, s39, 0
	s_add_u32 s50, s38, 0x4400000
	s_addc_u32 s51, s39, 0
	s_add_u32 s6, s38, 0x4200000
	s_addc_u32 s7, s39, 0
	s_add_u32 s18, s38, 0x97c2000
	s_addc_u32 s19, s39, 0
	s_add_u32 s4, s38, 0x53c2000
	s_addc_u32 s5, s39, 0
	s_add_i32 s24, 0, 0x20000
	v_mov_b64_e32 v[4:5], s[4:5]
	s_mov_b32 s14, 0
	v_mov_b32_e32 v2, s24
	v_mov_b64_e32 v[6:7], s[6:7]
	s_add_i32 s6, 0, 0x20010
	s_movk_i32 s24, 0x80
	s_movk_i32 s15, 0x400
	ds_write_b128 v2, v[4:7]
	v_mov_b32_e32 v2, s6
	v_mov_b64_e32 v[4:5], s[18:19]
	s_mov_b32 s25, 4
	s_add_i32 s6, 0, 0x20018
	ds_write_b64 v2, v[4:5]
	v_mov_b32_e32 v6, s6
	v_mov_b64_e32 v[2:3], s[24:25]
	v_mov_b64_e32 v[4:5], s[14:15]
	s_add_i32 s6, 0, 0x20028
	ds_write2_b64 v6, v[2:3], v[4:5] offset1:1
	v_mov_b32_e32 v2, s6
	s_mov_b32 s6, s50
	s_mov_b32 s7, s51
	v_mov_b32_e32 v6, 2
	v_mov_b32_e32 v7, 16
	s_add_i32 s18, 0, 0x20030
	v_mov_b64_e32 v[10:11], s[6:7]
	ds_write_b64 v2, v[6:7]
	v_mov_b32_e32 v2, s18
	v_mov_b64_e32 v[8:9], s[4:5]
	s_add_i32 s6, 0, 0x20040
	s_mov_b32 s19, 2
	ds_write_b128 v2, v[8:11]
	v_mov_b32_e32 v2, s6
	v_mov_b64_e32 v[4:5], s[22:23]
	s_movk_i32 s6, 0x200
	s_mov_b32 s18, s24
	s_mov_b32 s7, s15
	s_add_i32 s22, 0, 0x20048
	ds_write_b64 v2, v[4:5]
	v_mov_b32_e32 v6, s22
	v_mov_b64_e32 v[2:3], s[18:19]
	v_mov_b64_e32 v[4:5], s[6:7]
	s_add_i32 s6, 0, 0x20058
	ds_write2_b64 v6, v[2:3], v[4:5] offset1:1
	v_mov_b32_e32 v2, s6
	s_mov_b32 s6, s48
	s_mov_b32 s7, s49
	v_mov_b32_e32 v6, 0
	s_add_i32 s18, 0, 0x20060
	v_mov_b64_e32 v[10:11], s[6:7]
	ds_write_b64 v2, v[6:7]
	v_mov_b32_e32 v2, s18
	v_mov_b64_e32 v[8:9], s[4:5]
	s_add_i32 s6, 0, 0x20070
	ds_write_b128 v2, v[8:11]
	v_mov_b32_e32 v2, s6
	s_movk_i32 s6, 0x300
	s_mov_b32 s28, 5
	v_mov_b64_e32 v[4:5], s[20:21]
	s_mov_b32 s7, 12
	s_mov_b32 s18, s24
	s_add_i32 s20, 0, 0x20078
	s_mov_b32 s29, 16
	ds_write_b64 v2, v[4:5]
	v_mov_b32_e32 v6, s20
	v_mov_b64_e32 v[2:3], s[18:19]
	v_mov_b64_e32 v[4:5], s[6:7]
	s_add_i32 s6, 0, 0x20088
	ds_write2_b64 v6, v[2:3], v[4:5] offset1:1
	v_mov_b32_e32 v2, s6
	v_mov_b64_e32 v[8:9], s[28:29]
	s_add_i32 s6, 0, 0x20090
	ds_write_b64 v2, v[8:9]
	v_mov_b32_e32 v2, s46
	v_mov_b32_e32 v3, s47
	v_mov_b32_e32 v4, s48
	v_mov_b32_e32 v5, s49
	v_mov_b32_e32 v6, s6
	s_add_i32 s6, 0, 0x200a0
	s_mov_b32 s18, 8
	ds_write_b128 v6, v[2:5]
	v_mov_b32_e32 v2, s6
	v_mov_b64_e32 v[4:5], s[16:17]
	s_mov_b32 s6, s15
	s_mov_b32 s7, s18
	s_add_i32 s15, 0, 0x200a8
	ds_write_b64 v2, v[4:5]
	v_mov_b32_e32 v6, s15
	v_mov_b64_e32 v[2:3], s[18:19]
	v_mov_b64_e32 v[4:5], s[6:7]
	s_add_i32 s6, 0, 0x200b8
	ds_write2_b64 v6, v[2:3], v[4:5] offset1:1
	v_mov_b32_e32 v2, s6
	v_mov_b32_e32 v4, s4
	s_add_i32 s4, 0, 0x200c0
	ds_write_b64 v2, v[8:9]
	v_mov_b32_e32 v2, s44
	v_mov_b32_e32 v3, s45
	v_mov_b32_e32 v5, s5
	v_mov_b32_e32 v6, s4
	s_add_i32 s4, 0, 0x200d0
	ds_write_b128 v6, v[2:5]
	v_mov_b32_e32 v2, s4
	v_mov_b64_e32 v[4:5], s[12:13]
	s_movk_i32 s4, 0x410
	s_movk_i32 s7, 0x88
	s_mov_b32 s6, s19
	s_mov_b32 s5, s14
	s_add_i32 s12, 0, 0x200d8
	ds_write_b64 v2, v[4:5]
	v_mov_b32_e32 v6, s12
	v_mov_b64_e32 v[2:3], s[6:7]
	v_mov_b64_e32 v[4:5], s[4:5]
	s_add_i32 s4, 0, 0x200e8
	ds_write2_b64 v6, v[2:3], v[4:5] offset1:1
	v_mov_b32_e32 v6, 6
	v_mov_b32_e32 v2, s4
	ds_write_b64 v2, v[6:7]

.LBB0_490:
	v_ashrrev_i32_e32 v7, 31, v14
	v_lshrrev_b32_e32 v7, 26, v7
	v_add_u32_e32 v7, v14, v7
	v_ashrrev_i32_e32 v15, 6, v7
	v_bfe_i32 v7, v14, 27, 1
	v_lshlrev_b32_e32 v6, 4, v14
	v_lshrrev_b32_e32 v7, 22, v7
	v_add_u32_e32 v7, v6, v7
	v_and_b32_e32 v7, 0xfffffc00, v7
	v_sub_u32_e32 v7, v6, v7
	v_lshrrev_b32_e32 v8, 4, v7
	v_bitop3_b32 v8, v8, v7, 32 bitop3:0x6c
	v_ashrrev_i32_e32 v7, 31, v7
	v_lshrrev_b32_e32 v7, 26, v7
	v_add_u32_e32 v7, v8, v7
	v_ashrrev_i32_e32 v16, 6, v7
	v_lshlrev_b32_e32 v9, 3, v15
	v_mul_i32_i24_e32 v10, 64, v16
	v_and_b32_e32 v9, -16, v9
	v_sub_u32_e32 v8, v8, v10
	v_mov_b32_e32 v10, 1
	v_add_u32_e32 v7, v16, v9
	v_lshlrev_b32_e32 v9, 5, v15
	v_ashrrev_i16_sdwa v8, v10, sext(v8) dst_sel:DWORD dst_unused:UNUSED_PAD src0_sel:DWORD src1_sel:BYTE_0
	v_and_b32_e32 v9, 32, v9
	v_bfe_i32 v17, v8, 0, 16
	v_and_b32_e32 v12, 3, v16
	s_mov_b32 s5, 0x1fffe0
	v_add_lshl_u32 v9, v9, v17, 1
	v_add_u32_e32 v6, 0x2000, v6
	v_lshlrev_b32_e32 v8, 1, v7
	v_lshrrev_b32_e32 v11, 2, v7
	v_and_or_b32 v12, v7, s5, v12
	v_lshl_add_u32 v130, v7, 11, v9
	v_ashrrev_i32_e32 v7, 31, v6
	v_lshrrev_b32_e32 v7, 22, v7
	v_add_u32_e32 v7, v6, v7
	v_ashrrev_i32_e32 v18, 10, v7
	v_mul_i32_i24_e32 v7, 0x400, v18
	v_sub_u32_e32 v6, v6, v7
	v_and_b32_e32 v8, 24, v8
	v_and_b32_e32 v11, 4, v11
	v_lshrrev_b32_e32 v7, 4, v6
	v_or3_b32 v8, v12, v11, v8
	v_bitop3_b32 v6, v7, v6, 32 bitop3:0x6c
	v_lshl_add_u32 v132, v8, 11, v9
	v_ashrrev_i32_e32 v8, 31, v6
	v_lshrrev_b32_e32 v8, 26, v8
	v_add_u32_e32 v8, v6, v8
	v_lshlrev_b32_e32 v7, 3, v18
	v_ashrrev_i32_e32 v19, 6, v8
	v_and_b32_e32 v8, 0xc0, v8
	v_and_b32_e32 v7, -16, v7
	v_sub_u32_e32 v6, v6, v8
	s_ashr_i32 s4, s18, 6
	v_add_u32_e32 v7, v19, v7
	v_ashrrev_i16_sdwa v6, v10, sext(v6) dst_sel:DWORD dst_unused:UNUSED_PAD src0_sel:DWORD src1_sel:BYTE_0
	v_lshlrev_b32_e32 v9, 5, v18
	v_bfe_i32 v20, v6, 0, 16
	v_lshlrev_b32_e32 v6, 1, v7
	v_lshrrev_b32_e32 v8, 2, v7
	v_and_b32_e32 v10, 3, v19
	s_lshl_b32 s25, s4, 10
	v_and_b32_e32 v9, 32, v9
	v_and_b32_e32 v6, 24, v6
	v_and_b32_e32 v8, 4, v8
	v_and_or_b32 v10, v7, s5, v10
	s_add_i32 s49, s25, 0
	v_or3_b32 v6, v10, v8, v6
	v_add_lshl_u32 v8, v9, v20, 1
	s_add_i32 m0, s49, 0x10000
	v_readfirstlane_b32 s10, v4
	v_readfirstlane_b32 s11, v5
	v_lshl_add_u32 v136, v6, 11, v8
	v_lshl_add_u32 v134, v7, 11, v8
	s_add_i32 s58, s49, 0x2000
	s_add_i32 s59, s49, 0x4000
	s_add_i32 s60, s49, 0x6000
	s_and_saveexec_b64 s[96:97], s[26:27]
	s_cbranch_execz .Lmy_w_4
	s_add_u32 s98, s38, 0x1d6c5400
	s_addc_u32 s99, s39, 0
	v_mov_b32_e32 v234, 0
	s_mov_b32 s94, 0

.Lmy_w_4:
	s_or_b64 exec, exec, s[96:97]
	s_barrier
	global_load_lds_dwordx4 v132, s[10:11]
	s_add_i32 m0, s49, 0x12000
	s_ashr_i32 s5, s18, 8
	global_load_lds_dwordx4 v136, s[10:11]
	s_mov_b64 s[10:11], 0x40000
	v_lshl_add_u64 v[6:7], v[4:5], 0, s[10:11]
	s_add_i32 m0, s49, 0x14000
	v_readfirstlane_b32 s12, v6
	v_readfirstlane_b32 s13, v7
	v_lshl_add_u64 v[6:7], v[2:3], 0, s[10:11]
	v_mov_b32_e32 v139, 0
	v_mov_b32_e32 v133, v139
	v_mov_b32_e32 v137, v139
	v_mov_b32_e32 v131, v139
	global_load_lds_dwordx4 v132, s[12:13]
	s_add_i32 m0, s49, 0x16000
	v_mov_b32_e32 v135, v139
	global_load_lds_dwordx4 v136, s[12:13]
	v_readfirstlane_b32 s12, v2
	v_readfirstlane_b32 s13, v3
	s_mov_b32 m0, s49
	s_cmp_eq_u32 s5, 1
	s_mov_b32 s61, 0
	v_lshl_add_u64 v[12:13], v[4:5], 0, v[132:133]
	v_lshl_add_u64 v[10:11], v[4:5], 0, v[136:137]
	global_load_lds_dwordx4 v130, s[12:13]
	s_mov_b32 m0, s58
	v_lshl_add_u64 v[8:9], v[2:3], 0, v[134:135]
	global_load_lds_dwordx4 v134, s[12:13]
	v_readfirstlane_b32 s12, v6
	v_readfirstlane_b32 s13, v7
	s_mov_b32 m0, s59
	v_lshl_add_u64 v[6:7], v[2:3], 0, v[130:131]
	s_nop 2
	global_load_lds_dwordx4 v130, s[12:13]
	s_mov_b32 m0, s60
	s_nop 0
	global_load_lds_dwordx4 v134, s[12:13]
	s_cselect_b64 s[12:13], -1, 0
	s_cmp_lg_u32 s5, 1
	s_cbranch_scc1 .LBB0_492
	s_barrier

.LBB0_748:
	s_or_b64 exec, exec, s[6:7]
	s_waitcnt lgkmcnt(0)
.LBB0_749:
	s_cmp_lt_i32 s40, 8
	s_cselect_b64 s[6:7], -1, 0
	s_and_b64 s[8:9], s[6:7], s[4:5]
	s_andn2_b64 vcc, exec, s[8:9]
	s_cbranch_vccnz .LBB0_830
	s_and_saveexec_b64 s[4:5], s[26:27]
	s_cbranch_execz .LBB0_752
	s_add_u32 s6, s38, 0x152c2000
	s_addc_u32 s7, s39, 0
	s_waitcnt lgkmcnt(0)
	s_add_u32 s10, s38, 0x4700000
	s_addc_u32 s11, s39, 0
	s_add_i32 s12, 0, 0x20000
	v_mov_b32_e32 v2, s36
	v_mov_b32_e32 v3, s37
	v_mov_b32_e32 v4, s10
	v_mov_b32_e32 v5, s11
	v_mov_b32_e32 v6, s12
	s_mov_b32 s10, 0
	ds_write_b128 v6, v[2:5]
	s_add_i32 s12, 0, 0x20010
	v_mov_b64_e32 v[4:5], s[6:7]
	s_movk_i32 s6, 0x80
	s_movk_i32 s11, 0x400
	v_mov_b32_e32 v2, s12
	s_mov_b32 s7, 4
	s_add_i32 s12, 0, 0x20018
	ds_write_b64 v2, v[4:5]
	v_mov_b32_e32 v6, s12
	v_mov_b64_e32 v[2:3], s[6:7]
	v_mov_b64_e32 v[4:5], s[10:11]
	s_add_i32 s6, 0, 0x20028
	ds_write2_b64 v6, v[2:3], v[4:5] offset1:1
	v_mov_b32_e32 v2, 4
	v_mov_b32_e32 v3, 16
	v_mov_b32_e32 v4, s6
	ds_write_b64 v4, v[2:3]

.LBB0_933:
	s_or_b64 exec, exec, s[6:7]
	s_waitcnt lgkmcnt(0)
.LBB0_934:
	s_cmp_lt_i32 s40, 10
	s_cselect_b64 s[6:7], -1, 0
	s_and_b64 s[8:9], s[6:7], s[4:5]
	s_andn2_b64 vcc, exec, s[8:9]
	s_cbranch_vccnz .LBB0_1011
	s_and_saveexec_b64 s[4:5], s[26:27]
	s_cbranch_execz .LBB0_937
	s_waitcnt lgkmcnt(0)
	s_add_u32 s10, s38, 0x53c2000
	s_addc_u32 s11, s39, 0
	s_add_u32 s12, s38, 0xb00000
	s_addc_u32 s13, s39, 0
	s_add_u32 s6, s38, 0x97c2000
	s_addc_u32 s7, s39, 0
	v_mov_b32_e32 v4, s12
	s_add_i32 s12, 0, 0x20000
	v_mov_b32_e32 v2, s10
	v_mov_b32_e32 v3, s11
	v_mov_b32_e32 v5, s13
	v_mov_b32_e32 v6, s12
	s_mov_b32 s10, 0
	ds_write_b128 v6, v[2:5]
	s_add_i32 s12, 0, 0x20010
	v_mov_b64_e32 v[4:5], s[6:7]
	s_movk_i32 s6, 0x80
	s_movk_i32 s11, 0xb00
	v_mov_b32_e32 v2, s12
	s_mov_b32 s7, 22
	s_add_i32 s12, 0, 0x20018
	ds_write_b64 v2, v[4:5]
	v_mov_b32_e32 v6, s12
	v_mov_b64_e32 v[2:3], s[6:7]
	v_mov_b64_e32 v[4:5], s[10:11]
	s_add_i32 s6, 0, 0x20028
	ds_write2_b64 v6, v[2:3], v[4:5] offset1:1
	v_mov_b32_e32 v2, 1
	v_mov_b32_e32 v3, 16
	v_mov_b32_e32 v4, s6
	ds_write_b64 v4, v[2:3]

.LBB0_940:
	v_ashrrev_i32_e32 v7, 31, v14
	v_lshrrev_b32_e32 v7, 26, v7
	v_add_u32_e32 v7, v14, v7
	v_ashrrev_i32_e32 v15, 6, v7
	v_bfe_i32 v7, v14, 27, 1
	v_lshlrev_b32_e32 v6, 4, v14
	v_lshrrev_b32_e32 v7, 22, v7
	v_add_u32_e32 v7, v6, v7
	v_and_b32_e32 v7, 0xfffffc00, v7
	v_sub_u32_e32 v7, v6, v7
	v_lshrrev_b32_e32 v8, 4, v7
	v_bitop3_b32 v8, v8, v7, 32 bitop3:0x6c
	v_ashrrev_i32_e32 v7, 31, v7
	v_lshrrev_b32_e32 v7, 26, v7
	v_add_u32_e32 v7, v8, v7
	v_ashrrev_i32_e32 v16, 6, v7
	v_lshlrev_b32_e32 v9, 3, v15
	v_mul_i32_i24_e32 v10, 64, v16
	v_and_b32_e32 v9, -16, v9
	v_sub_u32_e32 v8, v8, v10
	v_mov_b32_e32 v10, 1
	v_add_u32_e32 v7, v16, v9
	v_lshlrev_b32_e32 v9, 5, v15
	v_ashrrev_i16_sdwa v8, v10, sext(v8) dst_sel:DWORD dst_unused:UNUSED_PAD src0_sel:DWORD src1_sel:BYTE_0
	v_and_b32_e32 v9, 32, v9
	v_bfe_i32 v17, v8, 0, 16
	v_and_b32_e32 v12, 3, v16
	s_mov_b32 s5, 0x1fffe0
	v_add_lshl_u32 v9, v9, v17, 1
	v_add_u32_e32 v6, 0x2000, v6
	v_lshlrev_b32_e32 v8, 1, v7
	v_lshrrev_b32_e32 v11, 2, v7
	v_and_or_b32 v12, v7, s5, v12
	v_lshl_add_u32 v130, v7, 11, v9
	v_ashrrev_i32_e32 v7, 31, v6
	v_lshrrev_b32_e32 v7, 22, v7
	v_add_u32_e32 v7, v6, v7
	v_ashrrev_i32_e32 v18, 10, v7
	v_mul_i32_i24_e32 v7, 0x400, v18
	v_sub_u32_e32 v6, v6, v7
	v_and_b32_e32 v8, 24, v8
	v_and_b32_e32 v11, 4, v11
	v_lshrrev_b32_e32 v7, 4, v6
	v_or3_b32 v8, v12, v11, v8
	v_bitop3_b32 v6, v7, v6, 32 bitop3:0x6c
	v_lshl_add_u32 v132, v8, 11, v9
	v_ashrrev_i32_e32 v8, 31, v6
	v_lshrrev_b32_e32 v8, 26, v8
	v_add_u32_e32 v8, v6, v8
	v_lshlrev_b32_e32 v7, 3, v18
	v_ashrrev_i32_e32 v19, 6, v8
	v_and_b32_e32 v8, 0xc0, v8
	v_and_b32_e32 v7, -16, v7
	v_sub_u32_e32 v6, v6, v8
	s_ashr_i32 s4, s12, 6
	v_add_u32_e32 v7, v19, v7
	v_ashrrev_i16_sdwa v6, v10, sext(v6) dst_sel:DWORD dst_unused:UNUSED_PAD src0_sel:DWORD src1_sel:BYTE_0
	v_lshlrev_b32_e32 v9, 5, v18
	v_bfe_i32 v20, v6, 0, 16
	v_lshlrev_b32_e32 v6, 1, v7
	v_lshrrev_b32_e32 v8, 2, v7
	v_and_b32_e32 v10, 3, v19
	s_lshl_b32 s29, s4, 10
	v_and_b32_e32 v9, 32, v9
	v_and_b32_e32 v6, 24, v6
	v_and_b32_e32 v8, 4, v8
	v_and_or_b32 v10, v7, s5, v10
	s_add_i32 s51, s29, 0
	v_or3_b32 v6, v10, v8, v6
	v_add_lshl_u32 v8, v9, v20, 1
	s_add_i32 m0, s51, 0x10000
	v_readfirstlane_b32 s10, v4
	v_readfirstlane_b32 s11, v5
	v_lshl_add_u32 v136, v6, 11, v8
	v_lshl_add_u32 v134, v7, 11, v8
	s_add_i32 s60, s51, 0x2000
	s_add_i32 s61, s51, 0x4000
	s_add_i32 s62, s51, 0x6000
	s_and_saveexec_b64 s[96:97], s[26:27]
	s_cbranch_execz .Lmy_w_8
	s_add_u32 s98, s38, 0x1d6c5400
	s_addc_u32 s99, s39, 0
	v_mov_b32_e32 v234, 0
	s_mov_b32 s94, 0

.Lmy_w_8:
	s_or_b64 exec, exec, s[96:97]
	s_barrier
	global_load_lds_dwordx4 v132, s[10:11]
	s_add_i32 m0, s51, 0x12000
	s_ashr_i32 s5, s12, 8
	global_load_lds_dwordx4 v136, s[10:11]
	s_mov_b64 s[10:11], 0x40000
	v_lshl_add_u64 v[6:7], v[4:5], 0, s[10:11]
	s_add_i32 m0, s51, 0x14000
	v_readfirstlane_b32 s14, v6
	v_readfirstlane_b32 s15, v7
	v_lshl_add_u64 v[6:7], v[2:3], 0, s[10:11]
	v_mov_b32_e32 v139, 0
	v_mov_b32_e32 v133, v139
	v_mov_b32_e32 v137, v139
	v_mov_b32_e32 v131, v139
	global_load_lds_dwordx4 v132, s[14:15]
	s_add_i32 m0, s51, 0x16000
	v_mov_b32_e32 v135, v139
	global_load_lds_dwordx4 v136, s[14:15]
	v_readfirstlane_b32 s14, v2
	v_readfirstlane_b32 s15, v3
	s_mov_b32 m0, s51
	s_cmp_eq_u32 s5, 1
	s_mov_b32 s13, 0
	v_lshl_add_u64 v[12:13], v[4:5], 0, v[132:133]
	v_lshl_add_u64 v[10:11], v[4:5], 0, v[136:137]
	global_load_lds_dwordx4 v130, s[14:15]
	s_mov_b32 m0, s60
	v_lshl_add_u64 v[8:9], v[2:3], 0, v[134:135]
	global_load_lds_dwordx4 v134, s[14:15]
	v_readfirstlane_b32 s14, v6
	v_readfirstlane_b32 s15, v7
	s_mov_b32 m0, s61
	v_lshl_add_u64 v[6:7], v[2:3], 0, v[130:131]
	s_nop 2
	global_load_lds_dwordx4 v130, s[14:15]
	s_mov_b32 m0, s62
	s_nop 0
	global_load_lds_dwordx4 v134, s[14:15]
	s_cselect_b64 s[14:15], -1, 0
	s_cmp_lg_u32 s5, 1
	s_cbranch_scc1 .LBB0_942
	s_barrier

.LBB0_1060:
	s_or_b64 exec, exec, s[6:7]
	s_waitcnt lgkmcnt(0)
.LBB0_1061:
	s_cmp_lt_i32 s40, 11
	s_cselect_b64 s[6:7], -1, 0
	s_and_b64 s[8:9], s[6:7], s[4:5]
	s_andn2_b64 vcc, exec, s[8:9]
	s_cbranch_vccnz .LBB0_1142
	s_and_saveexec_b64 s[4:5], s[26:27]
	s_cbranch_execz .LBB0_1064
	s_add_u32 s6, s38, 0x152c2000
	s_addc_u32 s7, s39, 0
	s_waitcnt lgkmcnt(0)
	s_add_u32 s10, s38, 0x97c2000
	s_addc_u32 s11, s39, 0
	s_add_u32 s12, s38, 0x3180000
	s_addc_u32 s13, s39, 0
	v_mov_b32_e32 v4, s12
	s_add_i32 s12, 0, 0x20000
	v_mov_b32_e32 v2, s10
	v_mov_b32_e32 v3, s11
	v_mov_b32_e32 v5, s13
	v_mov_b32_e32 v6, s12
	s_mov_b32 s10, 0
	ds_write_b128 v6, v[2:5]
	s_add_i32 s12, 0, 0x20010
	v_mov_b64_e32 v[4:5], s[6:7]
	s_movk_i32 s6, 0x80
	s_movk_i32 s11, 0x400
	v_mov_b32_e32 v2, s12
	s_mov_b32 s7, 4
	s_add_i32 s12, 0, 0x20018
	ds_write_b64 v2, v[4:5]
	v_mov_b32_e32 v6, s12
	v_mov_b64_e32 v[2:3], s[6:7]
	v_mov_b64_e32 v[4:5], s[10:11]
	s_add_i32 s6, 0, 0x20028
	ds_write2_b64 v6, v[2:3], v[4:5] offset1:1
	v_mov_b32_e32 v2, 4
	v_mov_b32_e32 v3, 44
	v_mov_b32_e32 v4, s6
	ds_write_b64 v4, v[2:3]

.LBB0_1067:
	v_ashrrev_i32_e32 v5, 31, v12
	v_lshrrev_b32_e32 v5, 26, v5
	v_add_u32_e32 v5, v12, v5
	v_ashrrev_i32_e32 v13, 6, v5
	v_bfe_i32 v5, v12, 27, 1
	v_lshlrev_b32_e32 v4, 4, v12
	v_lshrrev_b32_e32 v5, 22, v5
	v_add_u32_e32 v5, v4, v5
	v_and_b32_e32 v5, 0xfffffc00, v5
	v_sub_u32_e32 v5, v4, v5
	v_lshrrev_b32_e32 v6, 4, v5
	v_bitop3_b32 v6, v6, v5, 32 bitop3:0x6c
	v_ashrrev_i32_e32 v5, 31, v5
	v_lshrrev_b32_e32 v5, 26, v5
	v_lshlrev_b32_e32 v7, 3, v13
	v_add_u32_e32 v5, v6, v5
	v_and_b32_e32 v7, -16, v7
	v_ashrrev_i32_e32 v14, 6, v5
	v_add_u32_e32 v5, v14, v7
	v_lshlrev_b32_e32 v7, 5, v13
	v_and_b32_e32 v15, 32, v7
	v_mul_i32_i24_e32 v7, 64, v14
	v_sub_u32_e32 v6, v6, v7
	v_mov_b32_e32 v7, 1
	v_ashrrev_i16_sdwa v6, v7, sext(v6) dst_sel:DWORD dst_unused:UNUSED_PAD src0_sel:DWORD src1_sel:BYTE_0
	v_lshlrev_b32_e32 v8, 1, v5
	v_lshrrev_b32_e32 v9, 2, v5
	v_and_b32_e32 v10, 3, v14
	s_mov_b32 s5, 0xffffe0
	v_bfe_i32 v16, v6, 0, 16
	v_and_b32_e32 v8, 24, v8
	v_and_b32_e32 v9, 4, v9
	v_and_or_b32 v10, v5, s5, v10
	s_movk_i32 s7, 0xb00
	v_add_u32_e32 v6, v15, v16
	v_or3_b32 v8, v10, v9, v8
	v_mul_lo_u32 v5, v5, s7
	v_add_lshl_u32 v130, v6, v5, 1
	v_mul_u32_u24_e32 v5, 0xb00, v8
	v_add_u32_e32 v4, 0x2000, v4
	v_add_lshl_u32 v132, v5, v6, 1
	v_ashrrev_i32_e32 v5, 31, v4
	v_lshrrev_b32_e32 v5, 22, v5
	v_add_u32_e32 v5, v4, v5
	v_ashrrev_i32_e32 v17, 10, v5
	v_mul_i32_i24_e32 v5, 0x400, v17
	v_sub_u32_e32 v4, v4, v5
	v_lshrrev_b32_e32 v5, 4, v4
	v_bitop3_b32 v4, v5, v4, 32 bitop3:0x6c
	v_ashrrev_i32_e32 v6, 31, v4
	v_lshrrev_b32_e32 v6, 26, v6
	v_lshlrev_b32_e32 v5, 3, v17
	v_add_u32_e32 v6, v4, v6
	v_and_b32_e32 v5, -16, v5
	v_ashrrev_i32_e32 v19, 6, v6
	v_and_b32_e32 v6, 0xc0, v6
	v_add_u32_e32 v5, v19, v5
	v_lshlrev_b32_e32 v8, 5, v17
	v_sub_u32_e32 v4, v4, v6
	s_ashr_i32 s4, s6, 6
	v_and_b32_e32 v18, 32, v8
	v_ashrrev_i16_sdwa v4, v7, sext(v4) dst_sel:DWORD dst_unused:UNUSED_PAD src0_sel:DWORD src1_sel:BYTE_0
	v_lshlrev_b32_e32 v6, 1, v5
	v_lshrrev_b32_e32 v7, 2, v5
	v_and_b32_e32 v8, 3, v19
	v_bfe_i32 v20, v4, 0, 16
	v_and_b32_e32 v6, 24, v6
	v_and_b32_e32 v7, 4, v7
	v_and_or_b32 v8, v5, s5, v8
	s_lshl_b32 s23, s4, 10
	v_add_u32_e32 v4, v18, v20
	v_or3_b32 v6, v8, v7, v6
	v_mul_lo_u32 v5, v5, s7
	s_add_i32 s46, s23, 0
	v_add_lshl_u32 v134, v4, v5, 1
	v_mul_u32_u24_e32 v5, 0xb00, v6
	s_add_i32 m0, s46, 0x10000
	v_readfirstlane_b32 s10, v2
	v_readfirstlane_b32 s11, v3
	v_add_lshl_u32 v136, v5, v4, 1
	s_add_i32 s47, s46, 0x2000
	s_add_i32 s48, s46, 0x4000
	s_add_i32 s49, s46, 0x6000
	s_ashr_i32 s5, s6, 8
	s_and_saveexec_b64 s[96:97], s[26:27]
	s_cbranch_execz .Lmy_w_9
	s_add_u32 s98, s38, 0x1d6c5400
	s_addc_u32 s99, s39, 0
	v_mov_b32_e32 v234, 0
	s_mov_b32 s94, 0

.Lmy_w_9:
	s_or_b64 exec, exec, s[96:97]
	s_barrier
	global_load_lds_dwordx4 v132, s[10:11]
	s_add_i32 m0, s46, 0x12000
	v_mov_b32_e32 v139, 0
	global_load_lds_dwordx4 v136, s[10:11]
	s_mov_b64 s[10:11], 0xb0000
	v_lshl_add_u64 v[4:5], v[2:3], 0, s[10:11]
	s_add_i32 m0, s46, 0x14000
	v_readfirstlane_b32 s12, v4
	v_readfirstlane_b32 s13, v5
	v_lshl_add_u64 v[4:5], v[150:151], 0, s[10:11]
	v_mov_b32_e32 v133, v139
	v_mov_b32_e32 v137, v139
	v_mov_b32_e32 v131, v139
	v_mov_b32_e32 v135, v139
	global_load_lds_dwordx4 v132, s[12:13]
	s_add_i32 m0, s46, 0x16000
	s_cmp_eq_u32 s5, 1
	global_load_lds_dwordx4 v136, s[12:13]
	v_readfirstlane_b32 s12, v150
	v_readfirstlane_b32 s13, v151
	s_mov_b32 m0, s46
	s_mov_b32 s50, 0
	v_lshl_add_u64 v[10:11], v[2:3], 0, v[132:133]
	v_lshl_add_u64 v[8:9], v[2:3], 0, v[136:137]
	v_lshl_add_u64 v[6:7], v[150:151], 0, v[134:135]
	global_load_lds_dwordx4 v130, s[12:13]
	s_mov_b32 m0, s47
	s_nop 0
	global_load_lds_dwordx4 v134, s[12:13]
	v_readfirstlane_b32 s12, v4
	v_readfirstlane_b32 s13, v5
	s_mov_b32 m0, s48
	v_lshl_add_u64 v[4:5], v[150:151], 0, v[130:131]
	s_nop 2
	global_load_lds_dwordx4 v130, s[12:13]
	s_mov_b32 m0, s49
	s_nop 0
	global_load_lds_dwordx4 v134, s[12:13]
	s_cselect_b64 s[12:13], -1, 0
	s_cmp_lg_u32 s5, 1
	s_cbranch_scc1 .LBB0_1069
	s_barrier

.LBB0_1245:
	s_or_b64 exec, exec, s[6:7]
	s_waitcnt lgkmcnt(0)
.LBB0_1246:
	s_cmp_lt_i32 s40, 13
	s_cselect_b64 s[6:7], -1, 0
	s_and_b64 s[8:9], s[6:7], s[4:5]
	s_andn2_b64 vcc, exec, s[8:9]
	s_cbranch_vccnz .LBB0_1323
	s_and_saveexec_b64 s[4:5], s[26:27]
	s_cbranch_execz .LBB0_1249
	s_waitcnt lgkmcnt(0)
	s_add_u32 s10, s38, 0x53c2000
	s_addc_u32 s11, s39, 0
	s_add_u32 s12, s38, 0x1600000
	s_addc_u32 s13, s39, 0
	s_add_u32 s6, s38, 0x97c2000
	s_addc_u32 s7, s39, 0
	v_mov_b32_e32 v4, s12
	s_add_i32 s12, 0, 0x20000
	v_mov_b32_e32 v2, s10
	v_mov_b32_e32 v3, s11
	v_mov_b32_e32 v5, s13
	v_mov_b32_e32 v6, s12
	s_mov_b32 s10, 0
	ds_write_b128 v6, v[2:5]
	s_add_i32 s12, 0, 0x20010
	v_mov_b64_e32 v[4:5], s[6:7]
	s_movk_i32 s6, 0x80
	s_movk_i32 s11, 0xb00
	v_mov_b32_e32 v2, s12
	s_mov_b32 s7, 22
	s_add_i32 s12, 0, 0x20018
	ds_write_b64 v2, v[4:5]
	v_mov_b32_e32 v6, s12
	v_mov_b64_e32 v[2:3], s[6:7]
	v_mov_b64_e32 v[4:5], s[10:11]
	s_add_i32 s6, 0, 0x20028
	ds_write2_b64 v6, v[2:3], v[4:5] offset1:1
	v_mov_b32_e32 v2, 1
	v_mov_b32_e32 v3, 16
	v_mov_b32_e32 v4, s6
	ds_write_b64 v4, v[2:3]

.LBB0_1372:
	s_or_b64 exec, exec, s[6:7]
	s_waitcnt lgkmcnt(0)
.LBB0_1373:
	s_cmp_lt_i32 s40, 14
	s_cselect_b64 s[6:7], -1, 0
	s_and_b64 s[8:9], s[6:7], s[4:5]
	s_andn2_b64 vcc, exec, s[8:9]
	s_cbranch_vccnz .LBB0_1454
	s_and_saveexec_b64 s[4:5], s[26:27]
	s_cbranch_execz .LBB0_1376
	s_add_u32 s6, s38, 0x152c2000
	s_addc_u32 s7, s39, 0
	s_waitcnt lgkmcnt(0)
	s_add_u32 s10, s38, 0x97c2000
	s_addc_u32 s11, s39, 0
	s_add_u32 s12, s38, 0x3700000
	s_addc_u32 s13, s39, 0
	v_mov_b32_e32 v4, s12
	s_add_i32 s12, 0, 0x20000
	v_mov_b32_e32 v2, s10
	v_mov_b32_e32 v3, s11
	v_mov_b32_e32 v5, s13
	v_mov_b32_e32 v6, s12
	s_mov_b32 s10, 0
	ds_write_b128 v6, v[2:5]
	s_add_i32 s12, 0, 0x20010
	v_mov_b64_e32 v[4:5], s[6:7]
	s_movk_i32 s6, 0x80
	s_movk_i32 s11, 0x400
	v_mov_b32_e32 v2, s12
	s_mov_b32 s7, 4
	s_add_i32 s12, 0, 0x20018
	ds_write_b64 v2, v[4:5]
	v_mov_b32_e32 v6, s12
	v_mov_b64_e32 v[2:3], s[6:7]
	v_mov_b64_e32 v[4:5], s[10:11]
	s_add_i32 s6, 0, 0x20028
	ds_write2_b64 v6, v[2:3], v[4:5] offset1:1
	v_mov_b32_e32 v2, 4
	v_mov_b32_e32 v3, 44
	v_mov_b32_e32 v4, s6
	ds_write_b64 v4, v[2:3]

.LBB0_1557:
	s_or_b64 exec, exec, s[6:7]
	s_waitcnt lgkmcnt(0)
.LBB0_1558:
	s_cmp_lt_i32 s40, 16
	s_cselect_b64 s[6:7], -1, 0
	s_and_b64 s[8:9], s[6:7], s[4:5]
	s_andn2_b64 vcc, exec, s[8:9]
	s_cbranch_vccnz .LBB0_1635
	s_waitcnt lgkmcnt(0)
	s_and_saveexec_b64 s[10:11], s[26:27]
	s_cbranch_execz .LBB0_1561
	s_add_u32 s12, s38, 0xd7c2000
	s_addc_u32 s13, s39, 0
	s_add_u32 s18, s38, 0x4d00000
	s_addc_u32 s19, s39, 0
	s_add_u32 s4, s38, 0x53c2000
	s_addc_u32 s5, s39, 0
	s_add_u32 s6, s38, 0x4900000
	s_addc_u32 s7, s39, 0
	s_add_u32 s14, s38, 0x97c2000
	s_addc_u32 s15, s39, 0
	s_add_i32 s17, 0, 0x20000
	v_mov_b64_e32 v[4:5], s[4:5]
	v_mov_b32_e32 v2, s17
	v_mov_b64_e32 v[6:7], s[6:7]
	s_add_i32 s6, 0, 0x20010
	s_mov_b32 s16, 0
	ds_write_b128 v2, v[4:7]
	v_mov_b32_e32 v2, s6
	v_mov_b64_e32 v[4:5], s[14:15]
	s_movk_i32 s17, 0x400
	s_mov_b32 s15, 8
	s_movk_i32 s14, 0x80
	s_add_i32 s6, 0, 0x20018
	ds_write_b64 v2, v[4:5]
	v_mov_b32_e32 v6, s6
	v_mov_b64_e32 v[2:3], s[14:15]
	v_mov_b64_e32 v[4:5], s[16:17]
	s_add_i32 s6, 0, 0x20028
	ds_write2_b64 v6, v[2:3], v[4:5] offset1:1
	v_mov_b32_e32 v2, 3
	v_mov_b32_e32 v3, 16
	v_mov_b32_e32 v4, s6
	ds_write_b64 v4, v[2:3]
	s_mov_b32 s6, s18
	s_mov_b32 s7, s19
	s_add_i32 s15, 0, 0x20030
	v_mov_b64_e32 v[4:5], s[4:5]
	v_mov_b32_e32 v2, s15
	v_mov_b64_e32 v[6:7], s[6:7]
	s_add_i32 s4, 0, 0x20040
	ds_write_b128 v2, v[4:7]
	v_mov_b32_e32 v2, s4
	v_mov_b64_e32 v[4:5], s[12:13]
	s_mov_b32 s15, 4
	s_mov_b32 s16, s17
	s_add_i32 s4, 0, 0x20048
	ds_write_b64 v2, v[4:5]
	v_mov_b32_e32 v2, s4
	v_mov_b64_e32 v[4:5], s[14:15]
	v_mov_b64_e32 v[6:7], s[16:17]
	s_add_i32 s4, 0, 0x20058
	ds_write2_b64 v2, v[4:5], v[6:7] offset1:1
	v_mov_b32_e32 v2, 0
	v_mov_b32_e32 v4, s4
	ds_write_b64 v4, v[2:3]

.LBB0_1711:
	s_lshl_b32 s6, s3, 8
	s_add_u32 s6, s34, s6
	s_addc_u32 s7, s35, 0
	v_mov_b32_e32 v3, 0x1000
	v_mov_b32_e32 v5, 1
	global_atomic_add v5, v3, v5, s[6:7] offset:1024 sc0
	v_cvt_f32_u32_e32 v3, v4
	v_sub_u32_e32 v6, 0, v4
	v_rcp_iflag_f32_e32 v3, v3
	s_nop 0
	v_mul_f32_e32 v3, 0x4f7ffffe, v3
	v_cvt_u32_f32_e32 v3, v3
	v_mul_lo_u32 v6, v6, v3
	v_mul_hi_u32 v6, v3, v6
	v_add_u32_e32 v3, v3, v6
	s_waitcnt vmcnt(0)
	v_mul_hi_u32 v3, v5, v3
	v_mul_lo_u32 v6, v3, v4
	v_sub_u32_e32 v6, v5, v6
	v_add_u32_e32 v7, 1, v3
	v_cmp_ge_u32_e32 vcc, v6, v4
	v_add_u32_e32 v5, 1, v5
	s_nop 0
	v_cndmask_b32_e32 v3, v3, v7, vcc
	v_sub_u32_e32 v7, v6, v4
	v_cndmask_b32_e32 v6, v6, v7, vcc
	v_add_u32_e32 v7, 1, v3
	v_cmp_ge_u32_e32 vcc, v6, v4
	s_nop 1
	v_cndmask_b32_e32 v3, v3, v7, vcc
	v_mul_lo_u32 v6, v4, v3
	v_add_u32_e32 v4, v6, v4
	v_cmp_ne_u32_e32 vcc, v5, v4
	s_and_saveexec_b64 s[8:9], vcc
	s_xor_b64 s[8:9], exec, s[8:9]
	s_cbranch_execz .LBB0_1725
	s_waitcnt lgkmcnt(0)
	v_mad_u32_u24 v6, v3, v2, v2
	s_nop 0
	v_readfirstlane_b32 s95, v6
.LBB0_1725:
	s_andn2_saveexec_b64 s[8:9], s[8:9]
	s_cbranch_execz .LBB0_1743
	buffer_wbl2 sc1
	s_waitcnt lgkmcnt(0)
	v_mad_u32_u24 v6, v3, v2, v2
	s_waitcnt vmcnt(0)
	v_mov_b32_e32 v4, 0x1d6c5000
	v_mov_b32_e32 v5, 1
	global_atomic_add v4, v5, s[38:39] offset:1024
	v_readfirstlane_b32 s95, v6
.LBB0_1743:
	s_or_b64 exec, exec, s[4:5]
	s_waitcnt lgkmcnt(0)
.LBB0_1744:
	s_cmp_lt_i32 s40, 18
	s_cselect_b64 s[4:5], -1, 0
	s_and_b64 s[6:7], s[4:5], s[0:1]
	s_andn2_b64 vcc, exec, s[6:7]
	s_cbranch_vccnz .LBB0_1825
	s_and_saveexec_b64 s[0:1], s[26:27]
	s_cbranch_execz .LBB0_1747
	s_add_u32 s4, s38, 0x152c2000
	s_addc_u32 s5, s39, 0
	s_add_u32 s8, s38, 0x4f00000
	s_addc_u32 s9, s39, 0
	s_waitcnt lgkmcnt(0)
	s_add_i32 s10, 0, 0x20000
	v_mov_b32_e32 v2, s36
	v_mov_b32_e32 v3, s37
	v_mov_b32_e32 v4, s8
	v_mov_b32_e32 v5, s9
	v_mov_b32_e32 v6, s10
	s_mov_b32 s8, 0
	ds_write_b128 v6, v[2:5]
	s_add_i32 s10, 0, 0x20010
	v_mov_b64_e32 v[4:5], s[4:5]
	s_movk_i32 s4, 0x80
	s_movk_i32 s9, 0x400
	v_mov_b32_e32 v2, s10
	s_mov_b32 s5, 4
	s_add_i32 s10, 0, 0x20018
	ds_write_b64 v2, v[4:5]
	v_mov_b32_e32 v6, s10
	v_mov_b64_e32 v[2:3], s[4:5]
	v_mov_b64_e32 v[4:5], s[8:9]
	s_add_i32 s4, 0, 0x20028
	ds_write2_b64 v6, v[2:3], v[4:5] offset1:1
	v_mov_b32_e32 v2, 4
	v_mov_b32_e32 v3, 16
	v_mov_b32_e32 v4, s4
	ds_write_b64 v4, v[2:3]

.LBB0_1750:
	v_ashrrev_i32_e32 v7, 31, v14
	v_lshrrev_b32_e32 v7, 26, v7
	v_add_u32_e32 v7, v14, v7
	v_ashrrev_i32_e32 v15, 6, v7
	v_bfe_i32 v7, v14, 27, 1
	v_lshlrev_b32_e32 v6, 4, v14
	v_lshrrev_b32_e32 v7, 22, v7
	v_add_u32_e32 v7, v6, v7
	v_and_b32_e32 v7, 0xfffffc00, v7
	v_sub_u32_e32 v7, v6, v7
	v_lshrrev_b32_e32 v8, 4, v7
	v_bitop3_b32 v8, v8, v7, 32 bitop3:0x6c
	v_ashrrev_i32_e32 v7, 31, v7
	v_lshrrev_b32_e32 v7, 26, v7
	v_add_u32_e32 v7, v8, v7
	v_ashrrev_i32_e32 v16, 6, v7
	v_lshlrev_b32_e32 v9, 3, v15
	v_mul_i32_i24_e32 v10, 64, v16
	v_and_b32_e32 v9, -16, v9
	v_sub_u32_e32 v8, v8, v10
	v_mov_b32_e32 v10, 1
	v_add_u32_e32 v7, v16, v9
	v_lshlrev_b32_e32 v9, 5, v15
	v_ashrrev_i16_sdwa v8, v10, sext(v8) dst_sel:DWORD dst_unused:UNUSED_PAD src0_sel:DWORD src1_sel:BYTE_0
	v_and_b32_e32 v9, 32, v9
	v_bfe_i32 v17, v8, 0, 16
	v_and_b32_e32 v12, 3, v16
	s_mov_b32 s1, 0x1fffe0
	v_add_lshl_u32 v9, v9, v17, 1
	v_add_u32_e32 v6, 0x2000, v6
	v_lshlrev_b32_e32 v8, 1, v7
	v_lshrrev_b32_e32 v11, 2, v7
	v_and_or_b32 v12, v7, s1, v12
	v_lshl_add_u32 v130, v7, 11, v9
	v_ashrrev_i32_e32 v7, 31, v6
	v_lshrrev_b32_e32 v7, 22, v7
	v_add_u32_e32 v7, v6, v7
	v_ashrrev_i32_e32 v18, 10, v7
	v_mul_i32_i24_e32 v7, 0x400, v18
	v_sub_u32_e32 v6, v6, v7
	v_and_b32_e32 v8, 24, v8
	v_and_b32_e32 v11, 4, v11
	v_lshrrev_b32_e32 v7, 4, v6
	v_or3_b32 v8, v12, v11, v8
	v_bitop3_b32 v6, v7, v6, 32 bitop3:0x6c
	v_lshl_add_u32 v132, v8, 11, v9
	v_ashrrev_i32_e32 v8, 31, v6
	v_lshrrev_b32_e32 v8, 26, v8
	v_add_u32_e32 v8, v6, v8
	v_lshlrev_b32_e32 v7, 3, v18
	v_ashrrev_i32_e32 v19, 6, v8
	v_and_b32_e32 v8, 0xc0, v8
	v_and_b32_e32 v7, -16, v7
	v_sub_u32_e32 v6, v6, v8
	s_ashr_i32 s0, s16, 6
	v_add_u32_e32 v7, v19, v7
	v_ashrrev_i16_sdwa v6, v10, sext(v6) dst_sel:DWORD dst_unused:UNUSED_PAD src0_sel:DWORD src1_sel:BYTE_0
	v_lshlrev_b32_e32 v9, 5, v18
	v_bfe_i32 v20, v6, 0, 16
	v_lshlrev_b32_e32 v6, 1, v7
	v_lshrrev_b32_e32 v8, 2, v7
	v_and_b32_e32 v10, 3, v19
	s_lshl_b32 s23, s0, 10
	v_and_b32_e32 v9, 32, v9
	v_and_b32_e32 v6, 24, v6
	v_and_b32_e32 v8, 4, v8
	v_and_or_b32 v10, v7, s1, v10
	s_add_i32 s47, s23, 0
	v_or3_b32 v6, v10, v8, v6
	v_add_lshl_u32 v8, v9, v20, 1
	s_add_i32 m0, s47, 0x10000
	v_readfirstlane_b32 s8, v4
	v_readfirstlane_b32 s9, v5
	v_lshl_add_u32 v136, v6, 11, v8
	v_lshl_add_u32 v134, v7, 11, v8
	s_add_i32 s56, s47, 0x2000
	s_add_i32 s57, s47, 0x4000
	s_add_i32 s58, s47, 0x6000
	s_and_saveexec_b64 s[96:97], s[26:27]
	s_cbranch_execz .Lmy_w_16
	s_add_u32 s98, s38, 0x1d6c5400
	s_addc_u32 s99, s39, 0
	v_mov_b32_e32 v234, 0
	s_mov_b32 s94, 0

.Lmy_w_16:
	s_or_b64 exec, exec, s[96:97]
	s_barrier
	global_load_lds_dwordx4 v132, s[8:9]
	s_add_i32 m0, s47, 0x12000
	s_ashr_i32 s1, s16, 8
	global_load_lds_dwordx4 v136, s[8:9]
	s_mov_b64 s[8:9], 0x40000
	v_lshl_add_u64 v[6:7], v[4:5], 0, s[8:9]
	s_add_i32 m0, s47, 0x14000
	v_readfirstlane_b32 s10, v6
	v_readfirstlane_b32 s11, v7
	v_lshl_add_u64 v[6:7], v[2:3], 0, s[8:9]
	v_mov_b32_e32 v139, 0
	v_mov_b32_e32 v133, v139
	v_mov_b32_e32 v137, v139
	v_mov_b32_e32 v131, v139
	global_load_lds_dwordx4 v132, s[10:11]
	s_add_i32 m0, s47, 0x16000
	v_mov_b32_e32 v135, v139
	global_load_lds_dwordx4 v136, s[10:11]
	v_readfirstlane_b32 s10, v2
	v_readfirstlane_b32 s11, v3
	s_mov_b32 m0, s47
	s_cmp_eq_u32 s1, 1
	s_mov_b32 s59, 0
	v_lshl_add_u64 v[12:13], v[4:5], 0, v[132:133]
	v_lshl_add_u64 v[10:11], v[4:5], 0, v[136:137]
	global_load_lds_dwordx4 v130, s[10:11]
	s_mov_b32 m0, s56
	v_lshl_add_u64 v[8:9], v[2:3], 0, v[134:135]
	global_load_lds_dwordx4 v134, s[10:11]
	v_readfirstlane_b32 s10, v6
	v_readfirstlane_b32 s11, v7
	s_mov_b32 m0, s57
	v_lshl_add_u64 v[6:7], v[2:3], 0, v[130:131]
	s_nop 2
	global_load_lds_dwordx4 v130, s[10:11]
	s_mov_b32 m0, s58
	s_nop 0
	global_load_lds_dwordx4 v134, s[10:11]
	s_cselect_b64 s[10:11], -1, 0
	s_cmp_lg_u32 s1, 1
	s_cbranch_scc1 .LBB0_1752
	s_barrier

.LBB0_1928:
	s_or_b64 exec, exec, s[4:5]
	s_waitcnt lgkmcnt(0)
.LBB0_1929:
	s_cmp_lt_i32 s40, 20
	s_cselect_b64 s[4:5], -1, 0
	s_and_b64 s[6:7], s[4:5], s[0:1]
	s_andn2_b64 vcc, exec, s[6:7]
	s_cbranch_vccnz .LBB0_2006
	s_and_saveexec_b64 s[0:1], s[26:27]
	s_cbranch_execz .LBB0_1932
	s_add_u32 s8, s38, 0x53c2000
	s_addc_u32 s9, s39, 0
	s_waitcnt lgkmcnt(0)
	s_add_u32 s10, s38, 0x2100000
	s_addc_u32 s11, s39, 0
	s_add_u32 s4, s38, 0x97c2000
	s_addc_u32 s5, s39, 0
	v_mov_b32_e32 v4, s10
	s_add_i32 s10, 0, 0x20000
	v_mov_b32_e32 v2, s8
	v_mov_b32_e32 v3, s9
	v_mov_b32_e32 v5, s11
	v_mov_b32_e32 v6, s10
	s_mov_b32 s8, 0
	ds_write_b128 v6, v[2:5]
	s_add_i32 s10, 0, 0x20010
	v_mov_b64_e32 v[4:5], s[4:5]
	s_movk_i32 s4, 0x80
	s_movk_i32 s9, 0xb00
	v_mov_b32_e32 v2, s10
	s_mov_b32 s5, 22
	s_add_i32 s10, 0, 0x20018
	ds_write_b64 v2, v[4:5]
	v_mov_b32_e32 v6, s10
	v_mov_b64_e32 v[2:3], s[4:5]
	v_mov_b64_e32 v[4:5], s[8:9]
	s_add_i32 s4, 0, 0x20028
	ds_write2_b64 v6, v[2:3], v[4:5] offset1:1
	v_mov_b32_e32 v2, 1
	v_mov_b32_e32 v3, 16
	v_mov_b32_e32 v4, s4
	ds_write_b64 v4, v[2:3]

.LBB0_1935:
	v_ashrrev_i32_e32 v7, 31, v14
	v_lshrrev_b32_e32 v7, 26, v7
	v_add_u32_e32 v7, v14, v7
	v_ashrrev_i32_e32 v15, 6, v7
	v_bfe_i32 v7, v14, 27, 1
	v_lshlrev_b32_e32 v6, 4, v14
	v_lshrrev_b32_e32 v7, 22, v7
	v_add_u32_e32 v7, v6, v7
	v_and_b32_e32 v7, 0xfffffc00, v7
	v_sub_u32_e32 v7, v6, v7
	v_lshrrev_b32_e32 v8, 4, v7
	v_bitop3_b32 v8, v8, v7, 32 bitop3:0x6c
	v_ashrrev_i32_e32 v7, 31, v7
	v_lshrrev_b32_e32 v7, 26, v7
	v_add_u32_e32 v7, v8, v7
	v_ashrrev_i32_e32 v16, 6, v7
	v_lshlrev_b32_e32 v9, 3, v15
	v_mul_i32_i24_e32 v10, 64, v16
	v_and_b32_e32 v9, -16, v9
	v_sub_u32_e32 v8, v8, v10
	v_mov_b32_e32 v10, 1
	v_add_u32_e32 v7, v16, v9
	v_lshlrev_b32_e32 v9, 5, v15
	v_ashrrev_i16_sdwa v8, v10, sext(v8) dst_sel:DWORD dst_unused:UNUSED_PAD src0_sel:DWORD src1_sel:BYTE_0
	v_and_b32_e32 v9, 32, v9
	v_bfe_i32 v17, v8, 0, 16
	v_and_b32_e32 v12, 3, v16
	s_mov_b32 s1, 0x1fffe0
	v_add_lshl_u32 v9, v9, v17, 1
	v_add_u32_e32 v6, 0x2000, v6
	v_lshlrev_b32_e32 v8, 1, v7
	v_lshrrev_b32_e32 v11, 2, v7
	v_and_or_b32 v12, v7, s1, v12
	v_lshl_add_u32 v130, v7, 11, v9
	v_ashrrev_i32_e32 v7, 31, v6
	v_lshrrev_b32_e32 v7, 22, v7
	v_add_u32_e32 v7, v6, v7
	v_ashrrev_i32_e32 v18, 10, v7
	v_mul_i32_i24_e32 v7, 0x400, v18
	v_sub_u32_e32 v6, v6, v7
	v_and_b32_e32 v8, 24, v8
	v_and_b32_e32 v11, 4, v11
	v_lshrrev_b32_e32 v7, 4, v6
	v_or3_b32 v8, v12, v11, v8
	v_bitop3_b32 v6, v7, v6, 32 bitop3:0x6c
	v_lshl_add_u32 v132, v8, 11, v9
	v_ashrrev_i32_e32 v8, 31, v6
	v_lshrrev_b32_e32 v8, 26, v8
	v_add_u32_e32 v8, v6, v8
	v_lshlrev_b32_e32 v7, 3, v18
	v_ashrrev_i32_e32 v19, 6, v8
	v_and_b32_e32 v8, 0xc0, v8
	v_and_b32_e32 v7, -16, v7
	v_sub_u32_e32 v6, v6, v8
	s_ashr_i32 s0, s10, 6
	v_add_u32_e32 v7, v19, v7
	v_ashrrev_i16_sdwa v6, v10, sext(v6) dst_sel:DWORD dst_unused:UNUSED_PAD src0_sel:DWORD src1_sel:BYTE_0
	v_lshlrev_b32_e32 v9, 5, v18
	v_bfe_i32 v20, v6, 0, 16
	v_lshlrev_b32_e32 v6, 1, v7
	v_lshrrev_b32_e32 v8, 2, v7
	v_and_b32_e32 v10, 3, v19
	s_lshl_b32 s25, s0, 10
	v_and_b32_e32 v9, 32, v9
	v_and_b32_e32 v6, 24, v6
	v_and_b32_e32 v8, 4, v8
	v_and_or_b32 v10, v7, s1, v10
	s_add_i32 s49, s25, 0
	v_or3_b32 v6, v10, v8, v6
	v_add_lshl_u32 v8, v9, v20, 1
	s_add_i32 m0, s49, 0x10000
	v_readfirstlane_b32 s8, v4
	v_readfirstlane_b32 s9, v5
	v_lshl_add_u32 v136, v6, 11, v8
	v_lshl_add_u32 v134, v7, 11, v8
	s_add_i32 s58, s49, 0x2000
	s_add_i32 s59, s49, 0x4000
	s_add_i32 s60, s49, 0x6000
	s_and_saveexec_b64 s[96:97], s[26:27]
	s_cbranch_execz .Lmy_w_18
	s_add_u32 s98, s38, 0x1d6c5400
	s_addc_u32 s99, s39, 0
	v_mov_b32_e32 v234, 0
	s_mov_b32 s94, 0

.Lmy_w_18:
	s_or_b64 exec, exec, s[96:97]
	s_barrier
	global_load_lds_dwordx4 v132, s[8:9]
	s_add_i32 m0, s49, 0x12000
	s_ashr_i32 s1, s10, 8
	global_load_lds_dwordx4 v136, s[8:9]
	s_mov_b64 s[8:9], 0x40000
	v_lshl_add_u64 v[6:7], v[4:5], 0, s[8:9]
	s_add_i32 m0, s49, 0x14000
	v_readfirstlane_b32 s12, v6
	v_readfirstlane_b32 s13, v7
	v_lshl_add_u64 v[6:7], v[2:3], 0, s[8:9]
	v_mov_b32_e32 v139, 0
	v_mov_b32_e32 v133, v139
	v_mov_b32_e32 v137, v139
	v_mov_b32_e32 v131, v139
	global_load_lds_dwordx4 v132, s[12:13]
	s_add_i32 m0, s49, 0x16000
	v_mov_b32_e32 v135, v139
	global_load_lds_dwordx4 v136, s[12:13]
	v_readfirstlane_b32 s12, v2
	v_readfirstlane_b32 s13, v3
	s_mov_b32 m0, s49
	s_cmp_eq_u32 s1, 1
	s_mov_b32 s11, 0
	v_lshl_add_u64 v[12:13], v[4:5], 0, v[132:133]
	v_lshl_add_u64 v[10:11], v[4:5], 0, v[136:137]
	global_load_lds_dwordx4 v130, s[12:13]
	s_mov_b32 m0, s58
	v_lshl_add_u64 v[8:9], v[2:3], 0, v[134:135]
	global_load_lds_dwordx4 v134, s[12:13]
	v_readfirstlane_b32 s12, v6
	v_readfirstlane_b32 s13, v7
	s_mov_b32 m0, s59
	v_lshl_add_u64 v[6:7], v[2:3], 0, v[130:131]
	s_nop 2
	global_load_lds_dwordx4 v130, s[12:13]
	s_mov_b32 m0, s60
	s_nop 0
	global_load_lds_dwordx4 v134, s[12:13]
	s_cselect_b64 s[12:13], -1, 0
	s_cmp_lg_u32 s1, 1
	s_cbranch_scc1 .LBB0_1937
	s_barrier

.LBB0_2055:
	s_or_b64 exec, exec, s[4:5]
	s_waitcnt lgkmcnt(0)
.LBB0_2056:
	s_cmp_lt_i32 s40, 21
	s_cselect_b64 s[4:5], -1, 0
	s_and_b64 s[6:7], s[4:5], s[0:1]
	s_andn2_b64 vcc, exec, s[6:7]
	s_cbranch_vccnz .LBB0_2137
	s_and_saveexec_b64 s[0:1], s[26:27]
	s_cbranch_execz .LBB0_2059
	s_add_u32 s4, s38, 0x152c2000
	s_addc_u32 s5, s39, 0
	s_add_u32 s8, s38, 0x97c2000
	s_addc_u32 s9, s39, 0
	s_waitcnt lgkmcnt(0)
	s_add_u32 s10, s38, 0x3c80000
	s_addc_u32 s11, s39, 0
	v_mov_b32_e32 v4, s10
	s_add_i32 s10, 0, 0x20000
	v_mov_b32_e32 v2, s8
	v_mov_b32_e32 v3, s9
	v_mov_b32_e32 v5, s11
	v_mov_b32_e32 v6, s10
	s_mov_b32 s8, 0
	ds_write_b128 v6, v[2:5]
	s_add_i32 s10, 0, 0x20010
	v_mov_b64_e32 v[4:5], s[4:5]
	s_movk_i32 s4, 0x80
	s_movk_i32 s9, 0x400
	v_mov_b32_e32 v2, s10
	s_mov_b32 s5, 4
	s_add_i32 s10, 0, 0x20018
	ds_write_b64 v2, v[4:5]
	v_mov_b32_e32 v6, s10
	v_mov_b64_e32 v[2:3], s[4:5]
	v_mov_b64_e32 v[4:5], s[8:9]
	s_add_i32 s4, 0, 0x20028
	ds_write2_b64 v6, v[2:3], v[4:5] offset1:1
	v_mov_b32_e32 v2, 4
	v_mov_b32_e32 v3, 44
	v_mov_b32_e32 v4, s4
	ds_write_b64 v4, v[2:3]

.LBB0_2062:
	v_ashrrev_i32_e32 v5, 31, v12
	v_lshrrev_b32_e32 v5, 26, v5
	v_add_u32_e32 v5, v12, v5
	v_ashrrev_i32_e32 v13, 6, v5
	v_bfe_i32 v5, v12, 27, 1
	v_lshlrev_b32_e32 v4, 4, v12
	v_lshrrev_b32_e32 v5, 22, v5
	v_add_u32_e32 v5, v4, v5
	v_and_b32_e32 v5, 0xfffffc00, v5
	v_sub_u32_e32 v5, v4, v5
	v_lshrrev_b32_e32 v6, 4, v5
	v_bitop3_b32 v6, v6, v5, 32 bitop3:0x6c
	v_ashrrev_i32_e32 v5, 31, v5
	v_lshrrev_b32_e32 v5, 26, v5
	v_lshlrev_b32_e32 v7, 3, v13
	v_add_u32_e32 v5, v6, v5
	v_and_b32_e32 v7, -16, v7
	v_ashrrev_i32_e32 v14, 6, v5
	v_add_u32_e32 v5, v14, v7
	v_lshlrev_b32_e32 v7, 5, v13
	v_and_b32_e32 v15, 32, v7
	v_mul_i32_i24_e32 v7, 64, v14
	v_sub_u32_e32 v6, v6, v7
	v_mov_b32_e32 v7, 1
	v_ashrrev_i16_sdwa v6, v7, sext(v6) dst_sel:DWORD dst_unused:UNUSED_PAD src0_sel:DWORD src1_sel:BYTE_0
	v_lshlrev_b32_e32 v8, 1, v5
	v_lshrrev_b32_e32 v9, 2, v5
	v_and_b32_e32 v10, 3, v14
	s_mov_b32 s1, 0xffffe0
	v_bfe_i32 v16, v6, 0, 16
	v_and_b32_e32 v8, 24, v8
	v_and_b32_e32 v9, 4, v9
	v_and_or_b32 v10, v5, s1, v10
	s_movk_i32 s5, 0xb00
	v_add_u32_e32 v6, v15, v16
	v_or3_b32 v8, v10, v9, v8
	v_mul_lo_u32 v5, v5, s5
	v_add_lshl_u32 v130, v6, v5, 1
	v_mul_u32_u24_e32 v5, 0xb00, v8
	v_add_u32_e32 v4, 0x2000, v4
	v_add_lshl_u32 v132, v5, v6, 1
	v_ashrrev_i32_e32 v5, 31, v4
	v_lshrrev_b32_e32 v5, 22, v5
	v_add_u32_e32 v5, v4, v5
	v_ashrrev_i32_e32 v17, 10, v5
	v_mul_i32_i24_e32 v5, 0x400, v17
	v_sub_u32_e32 v4, v4, v5
	v_lshrrev_b32_e32 v5, 4, v4
	v_bitop3_b32 v4, v5, v4, 32 bitop3:0x6c
	v_ashrrev_i32_e32 v6, 31, v4
	v_lshrrev_b32_e32 v6, 26, v6
	v_lshlrev_b32_e32 v5, 3, v17
	v_add_u32_e32 v6, v4, v6
	v_and_b32_e32 v5, -16, v5
	v_ashrrev_i32_e32 v19, 6, v6
	v_and_b32_e32 v6, 0xc0, v6
	v_add_u32_e32 v5, v19, v5
	v_lshlrev_b32_e32 v8, 5, v17
	v_sub_u32_e32 v4, v4, v6
	s_ashr_i32 s0, s4, 6
	v_and_b32_e32 v18, 32, v8
	v_ashrrev_i16_sdwa v4, v7, sext(v4) dst_sel:DWORD dst_unused:UNUSED_PAD src0_sel:DWORD src1_sel:BYTE_0
	v_lshlrev_b32_e32 v6, 1, v5
	v_lshrrev_b32_e32 v7, 2, v5
	v_and_b32_e32 v8, 3, v19
	v_bfe_i32 v20, v4, 0, 16
	v_and_b32_e32 v6, 24, v6
	v_and_b32_e32 v7, 4, v7
	v_and_or_b32 v8, v5, s1, v8
	s_lshl_b32 s21, s0, 10
	v_add_u32_e32 v4, v18, v20
	v_or3_b32 v6, v8, v7, v6
	v_mul_lo_u32 v5, v5, s5
	s_add_i32 s44, s21, 0
	v_add_lshl_u32 v134, v4, v5, 1
	v_mul_u32_u24_e32 v5, 0xb00, v6
	s_add_i32 m0, s44, 0x10000
	v_readfirstlane_b32 s8, v2
	v_readfirstlane_b32 s9, v3
	v_add_lshl_u32 v136, v5, v4, 1
	s_add_i32 s45, s44, 0x2000
	s_add_i32 s46, s44, 0x4000
	s_add_i32 s47, s44, 0x6000
	s_ashr_i32 s1, s4, 8
	s_and_saveexec_b64 s[96:97], s[26:27]
	s_cbranch_execz .Lmy_w_19
	s_add_u32 s98, s38, 0x1d6c5400
	s_addc_u32 s99, s39, 0
	v_mov_b32_e32 v234, 0
	s_mov_b32 s94, 0

.Lmy_w_19:
	s_or_b64 exec, exec, s[96:97]
	s_barrier
	global_load_lds_dwordx4 v132, s[8:9]
	s_add_i32 m0, s44, 0x12000
	v_mov_b32_e32 v139, 0
	global_load_lds_dwordx4 v136, s[8:9]
	s_mov_b64 s[8:9], 0xb0000
	v_lshl_add_u64 v[4:5], v[2:3], 0, s[8:9]
	s_add_i32 m0, s44, 0x14000
	v_readfirstlane_b32 s10, v4
	v_readfirstlane_b32 s11, v5
	v_lshl_add_u64 v[4:5], v[150:151], 0, s[8:9]
	v_mov_b32_e32 v133, v139
	v_mov_b32_e32 v137, v139
	v_mov_b32_e32 v131, v139
	v_mov_b32_e32 v135, v139
	global_load_lds_dwordx4 v132, s[10:11]
	s_add_i32 m0, s44, 0x16000
	s_cmp_eq_u32 s1, 1
	global_load_lds_dwordx4 v136, s[10:11]
	v_readfirstlane_b32 s10, v150
	v_readfirstlane_b32 s11, v151
	s_mov_b32 m0, s44
	s_mov_b32 s48, 0
	v_lshl_add_u64 v[10:11], v[2:3], 0, v[132:133]
	v_lshl_add_u64 v[8:9], v[2:3], 0, v[136:137]
	v_lshl_add_u64 v[6:7], v[150:151], 0, v[134:135]
	global_load_lds_dwordx4 v130, s[10:11]
	s_mov_b32 m0, s45
	s_nop 0
	global_load_lds_dwordx4 v134, s[10:11]
	v_readfirstlane_b32 s10, v4
	v_readfirstlane_b32 s11, v5
	s_mov_b32 m0, s46
	v_lshl_add_u64 v[4:5], v[150:151], 0, v[130:131]
	s_nop 2
	global_load_lds_dwordx4 v130, s[10:11]
	s_mov_b32 m0, s47
	s_nop 0
	global_load_lds_dwordx4 v134, s[10:11]
	s_cselect_b64 s[10:11], -1, 0
	s_cmp_lg_u32 s1, 1
	s_cbranch_scc1 .LBB0_2064
	s_barrier
